# DPT95: diff units for qt<=95 processed as pairs of adjacent 64-query blocks sharing the K/V tile stream (longer units stay single), on top of PV3
# baseline (speedup 1.0000x reference)
.LBB0_692:
	s_and_b64 vcc, exec, s[4:5]
	s_cbranch_vccz .LBB0_709
	s_sub_i32 s0, s13, 40
	s_lshr_b32 s7, s0, 3
	s_sub_i32 s4, 0x7f, s7
	s_and_b32 s1, s4, 1
	s_cmp_eq_u32 s1, 0
	s_cbranch_scc0 .Ldp_go
	s_cmpk_le_u32 s4, 95
	s_cbranch_scc1 .Ldp_skip
.Ldp_go:
	s_waitcnt vmcnt(1)
	v_mov_b32_e32 v12, v156
	s_lshl_b32 s0, s4, 6
	v_ashrrev_i32_e32 v142, 7, v12
	s_and_b32 s6, s13, 7
	v_and_b32_e32 v141, 31, v12
	v_lshl_add_u32 v13, v142, 5, s0
	v_or_b32_e32 v128, v13, v141
	s_lshl_b32 s5, s6, 20
	v_readlane_b32 s0, v234, 46
	v_readlane_b32 s1, v234, 47
	s_add_u32 s0, s0, s5
	v_ashrrev_i32_e32 v129, 31, v128
	v_bfe_u32 v143, v12, 6, 1
	s_addc_u32 s1, s1, 0
	v_lshlrev_b64 v[2:3], 7, v[128:129]
	v_bfe_u32 v140, v12, 5, 1
	v_lshl_add_u64 v[2:3], s[0:1], 0, v[2:3]
	v_lshlrev_b32_e32 v130, 6, v143
	v_mov_b32_e32 v131, v1
	v_lshl_add_u64 v[2:3], v[2:3], 0, v[130:131]
	v_lshlrev_b32_e32 v132, 4, v140
	v_mov_b32_e32 v133, v1
	v_lshl_add_u64 v[2:3], v[2:3], 0, v[132:133]
	global_load_dwordx4 v[96:99], v[2:3], off
	global_load_dwordx4 v[100:103], v[2:3], off offset:32
	s_mov_b32 s16, 0xffffe000
	s_mov_b32 s17, -1
	v_lshl_add_u64 v[226:227], v[2:3], 0, s[16:17]
	global_load_dwordx4 v[184:187], v[226:227], off
	global_load_dwordx4 v[188:191], v[226:227], off offset:32
	v_readlane_b32 s0, v234, 44
	v_ashrrev_i32_e32 v2, 3, v12
	v_readlane_b32 s1, v234, 45
	s_add_u32 s0, s0, s5
	v_lshlrev_b32_e32 v0, 3, v12
	v_ashrrev_i32_e32 v3, 31, v2
	s_addc_u32 s1, s1, 0
	v_readlane_b32 s8, v234, 42
	v_and_b32_e32 v0, 56, v0
	v_lshlrev_b64 v[4:5], 7, v[2:3]
	v_readlane_b32 s9, v234, 43
	s_add_u32 s8, s8, s5
	v_lshl_add_u64 v[4:5], s[0:1], 0, v[4:5]
	v_lshlrev_b32_e32 v0, 1, v0
	s_addc_u32 s9, s9, 0
	v_lshl_add_u64 v[6:7], v[4:5], 0, v[0:1]
	v_lshlrev_b64 v[4:5], 14, v[2:3]
	v_lshl_add_u64 v[4:5], s[8:9], 0, v[4:5]
	v_add_u32_e32 v3, 0x100, v12
	v_lshl_add_u64 v[134:135], v[4:5], 0, v[0:1]
	v_ashrrev_i32_e32 v4, 3, v3
	v_ashrrev_i32_e32 v5, 31, v4
	v_lshlrev_b64 v[10:11], 14, v[4:5]
	v_lshlrev_b64 v[8:9], 7, v[4:5]
	v_lshl_add_u64 v[10:11], s[8:9], 0, v[10:11]
	v_lshl_add_u64 v[8:9], s[0:1], 0, v[8:9]
	v_lshl_add_u64 v[136:137], v[10:11], 0, v[0:1]
	s_barrier
	global_load_dwordx4 v[104:107], v[134:135], off
	v_lshl_add_u64 v[8:9], v[8:9], 0, v[0:1]
	global_load_dwordx4 v[108:111], v[6:7], off
	global_load_dwordx4 v[112:115], v[8:9], off
	global_load_dwordx4 v[116:119], v[136:137], off
	v_lshlrev_b32_e32 v3, 4, v12
	s_movk_i32 s5, 0x90
	v_and_b32_e32 v131, 0x70, v3
	v_mul_lo_u32 v133, v2, s5
	s_movk_i32 s8, 0x88
	v_mul_lo_u32 v144, v2, s8
	v_add_u32_e32 v3, v131, v133
	v_mul_lo_u32 v145, v4, s5
	v_mul_lo_u32 v146, v4, s8
	v_readfirstlane_b32 s5, v13
	s_cmpk_eq_i32 s7, 0x7f
	v_add3_u32 v5, v131, v144, s33
	v_add_u32_e32 v10, v131, v145
	v_add3_u32 v11, v131, v146, s33
	s_waitcnt vmcnt(2)
	ds_write_b128 v3, v[108:111]
	ds_write2_b64 v5, v[104:105], v[106:107] offset1:1
	s_waitcnt vmcnt(1)
	ds_write_b128 v10, v[112:115]
	s_waitcnt vmcnt(0)
	ds_write2_b64 v11, v[116:117], v[118:119] offset1:1
	s_cbranch_scc1 .LBB0_695
	v_add_co_u32_e32 v6, vcc, 0x2000, v6
	s_nop 1
	v_addc_co_u32_e32 v7, vcc, 0, v7, vcc
	v_add_co_u32_e32 v8, vcc, 0x2000, v8
	s_nop 1
	v_addc_co_u32_e32 v9, vcc, 0, v9, vcc
	global_load_dwordx4 v[108:111], v[6:7], off
	global_load_dwordx4 v[112:115], v[8:9], off
	global_load_dwordx4 v[104:107], v[134:135], off offset:128
	global_load_dwordx4 v[116:119], v[136:137], off offset:128
.LBB0_695:
	v_mov_b32_e32 v14, v1
	v_mov_b32_e32 v15, v1
	v_lshl_add_u64 v[138:139], s[0:1], 0, v[0:1]
	v_add_u32_e32 v150, 0x80, v4
	v_add_u32_e32 v151, 0x80, v2
	v_mov_b32_e32 v0, v1
	v_mov_b32_e32 v2, v1
	v_mov_b32_e32 v3, v1
	v_mov_b32_e32 v4, v1
	v_mov_b32_e32 v5, v1
	v_mov_b32_e32 v6, v1
	v_mov_b32_e32 v7, v1
	v_mov_b32_e32 v8, v1
	v_mov_b32_e32 v9, v1
	v_mov_b32_e32 v10, v1
	v_mov_b32_e32 v11, v1
	v_mov_b32_e32 v12, v1
	v_mov_b32_e32 v13, v1
	v_mov_b32_e32 v48, 0x42000000
	v_mov_b64_e32 v[30:31], v[14:15]
	v_mov_b64_e32 v[46:47], v[14:15]
	v_lshlrev_b32_e32 v147, 3, v140
	s_or_b32 s5, s5, 31
	v_mul_u32_u24_e32 v148, 0x90, v141
	v_lshlrev_b32_e32 v125, 2, v140
	v_mul_u32_u24_e32 v149, 0x88, v141
	s_mov_b32 s7, 0
	v_mov_b32_e32 v153, 0xc2000000
	v_mov_b32_e32 v152, 0
	v_mov_b64_e32 v[28:29], v[12:13]
	v_mov_b64_e32 v[26:27], v[10:11]
	v_mov_b64_e32 v[24:25], v[8:9]
	v_mov_b64_e32 v[22:23], v[6:7]
	v_mov_b64_e32 v[20:21], v[4:5]
	v_mov_b64_e32 v[18:19], v[2:3]
	v_mov_b64_e32 v[16:17], v[0:1]
	v_mov_b64_e32 v[44:45], v[12:13]
	v_mov_b64_e32 v[42:43], v[10:11]
	v_mov_b64_e32 v[40:41], v[8:9]
	v_mov_b64_e32 v[38:39], v[6:7]
	v_mov_b64_e32 v[36:37], v[4:5]
	v_mov_b64_e32 v[34:35], v[2:3]
	v_mov_b64_e32 v[32:33], v[0:1]
	s_mov_b32 s0, 0
	s_mov_b32 s8, 0
	v_mov_b32_e32 v49, v48
	v_mov_b32_e32 v50, v48
	v_mov_b32_e32 v51, v48
	v_mov_b32_e32 v52, v48
	v_mov_b32_e32 v53, v48
	v_mov_b32_e32 v54, v48
	v_mov_b32_e32 v55, v48
	v_mov_b32_e32 v56, v48
	v_mov_b32_e32 v57, v48
	v_mov_b32_e32 v58, v48
	v_mov_b32_e32 v59, v48
	v_mov_b32_e32 v60, v48
	v_mov_b32_e32 v61, v48
	v_mov_b32_e32 v62, v48
	v_mov_b32_e32 v63, v48
	s_and_b32 s10, s13, 7
	s_lshl_b32 s10, s10, 20
	v_readlane_b32 s16, v234, 44
	v_readlane_b32 s17, v234, 45
	v_readlane_b32 s11, v234, 42
	v_readlane_b32 s12, v234, 43
	s_add_u32 s16, s16, s10
	s_addc_u32 s17, s17, 0
	s_add_u32 s10, s11, s10
	s_addc_u32 s11, s12, 0
	s_add_u32 s18, s16, 0x4000
	s_addc_u32 s12, s17, 0
	s_add_u32 s16, s10, 0x100
	s_addc_u32 s17, s11, 0
	s_mov_b32 s10, s18
	s_mov_b32 s11, s12
	v_lshlrev_b32_e32 v180, 4, v156
	v_lshrrev_b32_e32 v182, 3, v156
	v_and_b32_e32 v183, 7, v156
	v_add_u32_e32 v181, 0x1000, v180
	v_lshlrev_b32_e32 v182, 14, v182
	v_lshl_add_u32 v182, v183, 4, v182
	v_add_u32_e32 v183, 0x80000, v182
	v_mov_b32_e32 v192, v1
	v_mov_b32_e32 v193, v1
	v_mov_b32_e32 v194, v1
	v_mov_b32_e32 v195, v1
	v_mov_b32_e32 v196, v1
	v_mov_b32_e32 v197, v1
	v_mov_b32_e32 v198, v1
	v_mov_b32_e32 v199, v1
	v_mov_b32_e32 v200, v1
	v_mov_b32_e32 v201, v1
	v_mov_b32_e32 v202, v1
	v_mov_b32_e32 v203, v1
	v_mov_b32_e32 v204, v1
	v_mov_b32_e32 v205, v1
	v_mov_b32_e32 v206, v1
	v_mov_b32_e32 v207, v1
	v_mov_b32_e32 v208, v1
	v_mov_b32_e32 v209, v1
	v_mov_b32_e32 v210, v1
	v_mov_b32_e32 v211, v1
	v_mov_b32_e32 v212, v1
	v_mov_b32_e32 v213, v1
	v_mov_b32_e32 v214, v1
	v_mov_b32_e32 v215, v1
	v_mov_b32_e32 v216, v1
	v_mov_b32_e32 v217, v1
	v_mov_b32_e32 v218, v1
	v_mov_b32_e32 v219, v1
	v_mov_b32_e32 v220, v1
	v_mov_b32_e32 v221, v1
	v_mov_b32_e32 v222, v1
	v_mov_b32_e32 v223, v1
	v_mov_b32_e32 v224, v1
	v_add_u32_e32 v225, 0xffffffc0, v128
	s_cmpk_le_u32 s4, 95
	s_cselect_b32 s18, 1, 0

.Ldp_A:
	s_cmp_eq_u32 s8, s4
	s_cbranch_scc1 .LBB0_707
	s_cmp_eq_u32 s18, 0
	s_cbranch_scc1 .LBB0_707
	v_add_u32_e32 v0, s14, v148
	v_add3_u32 v0, v0, v130, v132
	ds_read_b128 v[2:5], v0
	s_waitcnt lgkmcnt(0)
	v_mfma_f32_32x32x16_bf16 v[80:95], v[2:5], v[184:187], v[48:63]
	ds_read_b128 v[2:5], v0 offset:4608
	s_add_i32 s0, s7, 63
	v_cmp_le_i32_e32 vcc, s0, v225
	s_cmp_eq_u64 vcc, exec
	s_waitcnt lgkmcnt(0)
	v_mfma_f32_32x32x16_bf16 v[64:79], v[2:5], v[184:187], v[48:63]
	ds_read_b128 v[2:5], v0 offset:32
	s_waitcnt lgkmcnt(0)
	v_mfma_f32_32x32x16_bf16 v[80:95], v[2:5], v[188:191], v[80:95]
	ds_read_b128 v[2:5], v0 offset:4640
	s_waitcnt lgkmcnt(0)
	v_mfma_f32_32x32x16_bf16 v[64:79], v[2:5], v[188:191], v[64:79]
	s_cbranch_scc1 .Ldp_A705
	v_add_u32_e32 v0, s7, v125
	v_cmp_lt_i32_e32 vcc, v0, v225
	v_add_u32_e32 v2, 2, v0
	s_nop 4
	v_cndmask_b32_e32 v81, v169, v81, vcc
	v_cmp_le_i32_e32 vcc, v0, v225
	s_nop 1
	v_cndmask_b32_e32 v80, v169, v80, vcc
	v_cmp_le_i32_e32 vcc, v2, v225
	v_add_u32_e32 v2, 3, v0
	s_nop 0
	v_cndmask_b32_e32 v82, v169, v82, vcc
	v_cmp_le_i32_e32 vcc, v2, v225
	v_add_u32_e32 v2, 8, v0
	s_nop 0
	v_cndmask_b32_e32 v83, v169, v83, vcc
	v_cmp_le_i32_e32 vcc, v2, v225
	v_add_u32_e32 v2, 9, v0
	s_nop 0
	v_cndmask_b32_e32 v84, v169, v84, vcc
	v_cmp_le_i32_e32 vcc, v2, v225
	v_add_u32_e32 v2, 10, v0
	s_nop 0
	v_cndmask_b32_e32 v85, v169, v85, vcc
	v_cmp_le_i32_e32 vcc, v2, v225
	v_add_u32_e32 v2, 11, v0
	s_nop 0
	v_cndmask_b32_e32 v86, v169, v86, vcc
	v_cmp_le_i32_e32 vcc, v2, v225
	v_add_u32_e32 v2, 16, v0
	s_nop 0
	v_cndmask_b32_e32 v87, v169, v87, vcc
	v_cmp_le_i32_e32 vcc, v2, v225
	v_add_u32_e32 v2, 17, v0
	s_nop 0
	v_cndmask_b32_e32 v88, v169, v88, vcc
	v_cmp_le_i32_e32 vcc, v2, v225
	v_add_u32_e32 v2, 18, v0
	s_nop 0
	v_cndmask_b32_e32 v89, v169, v89, vcc
	v_cmp_le_i32_e32 vcc, v2, v225
	v_add_u32_e32 v2, 19, v0
	s_nop 0
	v_cndmask_b32_e32 v90, v169, v90, vcc
	v_cmp_le_i32_e32 vcc, v2, v225
	v_add_u32_e32 v2, 24, v0
	s_nop 0
	v_cndmask_b32_e32 v91, v169, v91, vcc
	v_cmp_le_i32_e32 vcc, v2, v225
	v_add_u32_e32 v2, 25, v0
	s_nop 0
	v_cndmask_b32_e32 v92, v169, v92, vcc
	v_cmp_le_i32_e32 vcc, v2, v225
	v_add_u32_e32 v2, 26, v0
	s_nop 0
	v_cndmask_b32_e32 v93, v169, v93, vcc
	v_cmp_le_i32_e32 vcc, v2, v225
	v_add_u32_e32 v2, 27, v0
	s_nop 0
	v_cndmask_b32_e32 v94, v169, v94, vcc
	v_cmp_le_i32_e32 vcc, v2, v225
	v_add_u32_e32 v2, 32, v0
	s_nop 0
	v_cndmask_b32_e32 v95, v169, v95, vcc
	v_cmp_le_i32_e32 vcc, v2, v225
	v_add_u32_e32 v2, 33, v0
	s_nop 0
	v_cndmask_b32_e32 v64, v169, v64, vcc
	v_cmp_le_i32_e32 vcc, v2, v225
	v_add_u32_e32 v2, 34, v0
	s_nop 0
	v_cndmask_b32_e32 v65, v169, v65, vcc
	v_cmp_le_i32_e32 vcc, v2, v225
	v_add_u32_e32 v2, 35, v0
	s_nop 0
	v_cndmask_b32_e32 v66, v169, v66, vcc
	v_cmp_le_i32_e32 vcc, v2, v225
	v_add_u32_e32 v2, 40, v0
	s_nop 0
	v_cndmask_b32_e32 v67, v169, v67, vcc
	v_cmp_le_i32_e32 vcc, v2, v225
	v_add_u32_e32 v2, 41, v0
	s_nop 0
	v_cndmask_b32_e32 v68, v169, v68, vcc
	v_cmp_le_i32_e32 vcc, v2, v225
	v_add_u32_e32 v2, 42, v0
	s_nop 0
	v_cndmask_b32_e32 v69, v169, v69, vcc
	v_cmp_le_i32_e32 vcc, v2, v225
	v_add_u32_e32 v2, 43, v0
	s_nop 0
	v_cndmask_b32_e32 v70, v169, v70, vcc
	v_cmp_le_i32_e32 vcc, v2, v225
	v_add_u32_e32 v2, 48, v0
	s_nop 0
	v_cndmask_b32_e32 v71, v169, v71, vcc
	v_cmp_le_i32_e32 vcc, v2, v225
	v_add_u32_e32 v2, 49, v0
	s_nop 0
	v_cndmask_b32_e32 v72, v169, v72, vcc
	v_cmp_le_i32_e32 vcc, v2, v225
	v_add_u32_e32 v2, 50, v0
	s_nop 0
	v_cndmask_b32_e32 v73, v169, v73, vcc
	v_cmp_le_i32_e32 vcc, v2, v225
	v_add_u32_e32 v2, 51, v0
	s_nop 0
	v_cndmask_b32_e32 v74, v169, v74, vcc
	v_cmp_le_i32_e32 vcc, v2, v225
	v_add_u32_e32 v2, 56, v0
	s_nop 0
	v_cndmask_b32_e32 v75, v169, v75, vcc
	v_cmp_le_i32_e32 vcc, v2, v225
	v_add_u32_e32 v2, 57, v0
	s_nop 0
	v_cndmask_b32_e32 v76, v169, v76, vcc
	v_cmp_le_i32_e32 vcc, v2, v225
	v_add_u32_e32 v2, 58, v0
	v_add_u32_e32 v0, 59, v0
	v_cndmask_b32_e32 v77, v169, v77, vcc
	v_cmp_le_i32_e32 vcc, v2, v225
	s_nop 1
	v_cndmask_b32_e32 v78, v169, v78, vcc
	v_cmp_gt_i32_e32 vcc, v0, v225
	s_and_saveexec_b64 s[0:1], vcc
	v_mov_b32_e32 v79, 0xf149f2ca
	s_or_b64 exec, exec, s[0:1]
